# dt-weight staging in both rowstat phases: 64 independent loads per thread in two batches instead of 16 dependent load-wait round trips
# speedup vs baseline: 1.0121x; 1.0121x over previous
.LBB0_75:
	s_load_dwordx16 s[4:19], s[0:1], 0x0
	v_mov_b32_e32 v4, v148
	s_movk_i32 s0, 0x2000
	s_waitcnt lgkmcnt(0)
	v_writelane_b32 v159, s4, 61
	v_cmp_gt_i32_e32 vcc, s0, v4
	v_and_b32_e32 v10, 7, v4
	v_writelane_b32 v158, s7, 0
	v_writelane_b32 v158, s8, 1
	v_writelane_b32 v158, s9, 2
	v_writelane_b32 v158, s10, 3
	v_writelane_b32 v158, s11, 4
	v_writelane_b32 v158, s12, 5
	v_writelane_b32 v158, s13, 6
	v_writelane_b32 v158, s14, 7
	v_writelane_b32 v158, s15, 8
	v_writelane_b32 v158, s16, 9
	v_writelane_b32 v158, s17, 10
	v_writelane_b32 v159, s5, 62
	v_writelane_b32 v158, s18, 11
	v_writelane_b32 v159, s6, 63
	v_writelane_b32 v158, s19, 12
	s_barrier
	s_and_saveexec_b64 s[0:1], vcc
	v_readlane_b32 s55, v159, 52
	s_cbranch_execz .LBB0_87
	s_lshl_b64 s[4:5], s[2:3], 2
	v_readlane_b32 s8, v159, 4
	v_readlane_b32 s9, v159, 5
	s_add_u32 s4, s8, s4
	v_readlane_b32 s10, v159, 6
	s_addc_u32 s5, s9, s5
	v_readlane_b32 s11, v159, 7
	s_add_u32 s6, s10, s54
	s_addc_u32 s7, s11, s33
	v_lshlrev_b32_e32 v8, 2, v10
	v_mov_b32_e32 v9, 0
	v_max_i32_e32 v1, 0x1f00, v4
	v_lshl_add_u64 v[2:3], s[6:7], 0, v[8:9]
	s_mov_b64 s[6:7], 0x1800
	v_sub_u32_e32 v1, v1, v4
	v_lshl_add_u64 v[2:3], v[2:3], 0, s[6:7]
	v_readlane_b32 s12, v159, 8
	v_readlane_b32 s13, v159, 9
	v_readlane_b32 s14, v159, 10
	v_readlane_b32 s15, v159, 11
	v_readlane_b32 s16, v159, 12
	v_readlane_b32 s17, v159, 13
	v_readlane_b32 s18, v159, 14
	v_readlane_b32 s19, v159, 15
	v_readlane_b32 s20, v159, 16
	v_readlane_b32 s21, v159, 17
	v_readlane_b32 s22, v159, 18
	v_readlane_b32 s23, v159, 19
	v_ashrrev_i32_e32 v6, 3, v4
	s_movk_i32 s8, 0x5420
	v_mad_i64_i32 v[8:9], s[10:11], v6, s8, v[2:3]
	v_ashrrev_i32_e32 v7, 31, v6
	v_lshl_add_u64 v[6:7], v[6:7], 2, s[4:5]
	s_mov_b64 s[12:13], 0xa8400
	v_lshlrev_b32_e32 v5, 2, v4
	global_load_dword v64, v[8:9], off
	global_load_dword v96, v[6:7], off
	v_lshl_add_u64 v[8:9], v[8:9], 0, s[12:13]
	global_load_dword v65, v[8:9], off
	global_load_dword v97, v[6:7], off offset:128
	v_lshl_add_u64 v[8:9], v[8:9], 0, s[12:13]
	global_load_dword v66, v[8:9], off
	global_load_dword v98, v[6:7], off offset:256
	v_lshl_add_u64 v[8:9], v[8:9], 0, s[12:13]
	global_load_dword v67, v[8:9], off
	global_load_dword v99, v[6:7], off offset:384
	v_lshl_add_u64 v[8:9], v[8:9], 0, s[12:13]
	global_load_dword v68, v[8:9], off
	global_load_dword v100, v[6:7], off offset:512
	v_lshl_add_u64 v[8:9], v[8:9], 0, s[12:13]
	global_load_dword v69, v[8:9], off
	global_load_dword v101, v[6:7], off offset:640
	v_lshl_add_u64 v[8:9], v[8:9], 0, s[12:13]
	global_load_dword v70, v[8:9], off
	global_load_dword v102, v[6:7], off offset:768
	v_lshl_add_u64 v[8:9], v[8:9], 0, s[12:13]
	global_load_dword v71, v[8:9], off
	global_load_dword v103, v[6:7], off offset:896
	v_lshl_add_u64 v[8:9], v[8:9], 0, s[12:13]
	global_load_dword v72, v[8:9], off
	global_load_dword v104, v[6:7], off offset:1024
	v_lshl_add_u64 v[8:9], v[8:9], 0, s[12:13]
	global_load_dword v73, v[8:9], off
	global_load_dword v105, v[6:7], off offset:1152
	v_lshl_add_u64 v[8:9], v[8:9], 0, s[12:13]
	global_load_dword v74, v[8:9], off
	global_load_dword v106, v[6:7], off offset:1280
	v_lshl_add_u64 v[8:9], v[8:9], 0, s[12:13]
	global_load_dword v75, v[8:9], off
	global_load_dword v107, v[6:7], off offset:1408
	v_lshl_add_u64 v[8:9], v[8:9], 0, s[12:13]
	global_load_dword v76, v[8:9], off
	global_load_dword v108, v[6:7], off offset:1536
	v_lshl_add_u64 v[8:9], v[8:9], 0, s[12:13]
	global_load_dword v77, v[8:9], off
	global_load_dword v109, v[6:7], off offset:1664
	v_lshl_add_u64 v[8:9], v[8:9], 0, s[12:13]
	global_load_dword v78, v[8:9], off
	global_load_dword v110, v[6:7], off offset:1792
	v_lshl_add_u64 v[8:9], v[8:9], 0, s[12:13]
	global_load_dword v79, v[8:9], off
	global_load_dword v111, v[6:7], off offset:1920
	v_lshl_add_u64 v[8:9], v[8:9], 0, s[12:13]
	s_waitcnt vmcnt(0)
	v_mul_f32_e32 v64, v64, v96
	ds_write_b32 v5, v64
	v_mul_f32_e32 v65, v65, v97
	ds_write_b32 v5, v65 offset:1024
	v_mul_f32_e32 v66, v66, v98
	ds_write_b32 v5, v66 offset:2048
	v_mul_f32_e32 v67, v67, v99
	ds_write_b32 v5, v67 offset:3072
	v_mul_f32_e32 v68, v68, v100
	ds_write_b32 v5, v68 offset:4096
	v_mul_f32_e32 v69, v69, v101
	ds_write_b32 v5, v69 offset:5120
	v_mul_f32_e32 v70, v70, v102
	ds_write_b32 v5, v70 offset:6144
	v_mul_f32_e32 v71, v71, v103
	ds_write_b32 v5, v71 offset:7168
	v_mul_f32_e32 v72, v72, v104
	ds_write_b32 v5, v72 offset:8192
	v_mul_f32_e32 v73, v73, v105
	ds_write_b32 v5, v73 offset:9216
	v_mul_f32_e32 v74, v74, v106
	ds_write_b32 v5, v74 offset:10240
	v_mul_f32_e32 v75, v75, v107
	ds_write_b32 v5, v75 offset:11264
	v_mul_f32_e32 v76, v76, v108
	ds_write_b32 v5, v76 offset:12288
	v_mul_f32_e32 v77, v77, v109
	ds_write_b32 v5, v77 offset:13312
	v_mul_f32_e32 v78, v78, v110
	ds_write_b32 v5, v78 offset:14336
	v_mul_f32_e32 v79, v79, v111
	ds_write_b32 v5, v79 offset:15360
	global_load_dword v80, v[8:9], off
	global_load_dword v112, v[6:7], off offset:2048
	v_lshl_add_u64 v[8:9], v[8:9], 0, s[12:13]
	global_load_dword v81, v[8:9], off
	global_load_dword v113, v[6:7], off offset:2176
	v_lshl_add_u64 v[8:9], v[8:9], 0, s[12:13]
	global_load_dword v82, v[8:9], off
	global_load_dword v114, v[6:7], off offset:2304
	v_lshl_add_u64 v[8:9], v[8:9], 0, s[12:13]
	global_load_dword v83, v[8:9], off
	global_load_dword v115, v[6:7], off offset:2432
	v_lshl_add_u64 v[8:9], v[8:9], 0, s[12:13]
	global_load_dword v84, v[8:9], off
	global_load_dword v116, v[6:7], off offset:2560
	v_lshl_add_u64 v[8:9], v[8:9], 0, s[12:13]
	global_load_dword v85, v[8:9], off
	global_load_dword v117, v[6:7], off offset:2688
	v_lshl_add_u64 v[8:9], v[8:9], 0, s[12:13]
	global_load_dword v86, v[8:9], off
	global_load_dword v118, v[6:7], off offset:2816
	v_lshl_add_u64 v[8:9], v[8:9], 0, s[12:13]
	global_load_dword v87, v[8:9], off
	global_load_dword v119, v[6:7], off offset:2944
	v_lshl_add_u64 v[8:9], v[8:9], 0, s[12:13]
	global_load_dword v88, v[8:9], off
	global_load_dword v120, v[6:7], off offset:3072
	v_lshl_add_u64 v[8:9], v[8:9], 0, s[12:13]
	global_load_dword v89, v[8:9], off
	global_load_dword v121, v[6:7], off offset:3200
	v_lshl_add_u64 v[8:9], v[8:9], 0, s[12:13]
	global_load_dword v90, v[8:9], off
	global_load_dword v122, v[6:7], off offset:3328
	v_lshl_add_u64 v[8:9], v[8:9], 0, s[12:13]
	global_load_dword v91, v[8:9], off
	global_load_dword v123, v[6:7], off offset:3456
	v_lshl_add_u64 v[8:9], v[8:9], 0, s[12:13]
	global_load_dword v92, v[8:9], off
	global_load_dword v124, v[6:7], off offset:3584
	v_lshl_add_u64 v[8:9], v[8:9], 0, s[12:13]
	global_load_dword v93, v[8:9], off
	global_load_dword v125, v[6:7], off offset:3712
	v_lshl_add_u64 v[8:9], v[8:9], 0, s[12:13]
	global_load_dword v94, v[8:9], off
	global_load_dword v126, v[6:7], off offset:3840
	v_lshl_add_u64 v[8:9], v[8:9], 0, s[12:13]
	global_load_dword v95, v[8:9], off
	global_load_dword v127, v[6:7], off offset:3968
	s_waitcnt vmcnt(0)
	v_mul_f32_e32 v80, v80, v112
	ds_write_b32 v5, v80 offset:16384
	v_mul_f32_e32 v81, v81, v113
	ds_write_b32 v5, v81 offset:17408
	v_mul_f32_e32 v82, v82, v114
	ds_write_b32 v5, v82 offset:18432
	v_mul_f32_e32 v83, v83, v115
	ds_write_b32 v5, v83 offset:19456
	v_mul_f32_e32 v84, v84, v116
	ds_write_b32 v5, v84 offset:20480
	v_mul_f32_e32 v85, v85, v117
	ds_write_b32 v5, v85 offset:21504
	v_mul_f32_e32 v86, v86, v118
	ds_write_b32 v5, v86 offset:22528
	v_mul_f32_e32 v87, v87, v119
	ds_write_b32 v5, v87 offset:23552
	v_mul_f32_e32 v88, v88, v120
	ds_write_b32 v5, v88 offset:24576
	v_mul_f32_e32 v89, v89, v121
	ds_write_b32 v5, v89 offset:25600
	v_mul_f32_e32 v90, v90, v122
	ds_write_b32 v5, v90 offset:26624
	v_mul_f32_e32 v91, v91, v123
	ds_write_b32 v5, v91 offset:27648
	v_mul_f32_e32 v92, v92, v124
	ds_write_b32 v5, v92 offset:28672
	v_mul_f32_e32 v93, v93, v125
	ds_write_b32 v5, v93 offset:29696
	v_mul_f32_e32 v94, v94, v126
	ds_write_b32 v5, v94 offset:30720
	v_mul_f32_e32 v95, v95, v127
	ds_write_b32 v5, v95 offset:31744

.LBB0_752:
	v_mov_b32_e32 v0, v148
	s_movk_i32 s2, 0x2000
	s_nop 0
	v_cmp_gt_i32_e32 vcc, s2, v0
	s_waitcnt vmcnt(0)
	v_and_b32_e32 v8, 7, v0
	s_barrier
	s_and_saveexec_b64 s[2:3], vcc
	s_cbranch_execz .LBB0_764
	s_lshl_b64 s[0:1], s[0:1], 2
	v_readlane_b32 s4, v159, 4
	v_readlane_b32 s5, v159, 5
	s_add_u32 s0, s4, s0
	v_readlane_b32 s6, v159, 6
	s_addc_u32 s1, s5, s1
	v_readlane_b32 s7, v159, 7
	s_add_u32 s4, s6, s28
	s_addc_u32 s5, s7, s26
	v_lshlrev_b32_e32 v6, 2, v8
	v_mov_b32_e32 v7, 0
	v_max_i32_e32 v1, 0x1f00, v0
	v_lshl_add_u64 v[2:3], s[4:5], 0, v[6:7]
	s_mov_b64 s[4:5], 0x1800
	v_sub_u32_e32 v1, v1, v0
	v_lshl_add_u64 v[2:3], v[2:3], 0, s[4:5]
	v_readlane_b32 s8, v159, 8
	v_readlane_b32 s9, v159, 9
	v_readlane_b32 s10, v159, 10
	v_readlane_b32 s11, v159, 11
	v_readlane_b32 s12, v159, 12
	v_readlane_b32 s13, v159, 13
	v_readlane_b32 s14, v159, 14
	v_readlane_b32 s15, v159, 15
	v_readlane_b32 s16, v159, 16
	v_readlane_b32 s17, v159, 17
	v_readlane_b32 s18, v159, 18
	v_readlane_b32 s19, v159, 19
	v_ashrrev_i32_e32 v6, 3, v0
	s_movk_i32 s4, 0x5420
	v_mad_i64_i32 v[10:11], s[6:7], v6, s4, v[2:3]
	v_ashrrev_i32_e32 v7, 31, v6
	v_lshl_add_u64 v[6:7], v[6:7], 2, s[0:1]
	s_mov_b64 s[8:9], 0xa8400
	v_lshlrev_b32_e32 v4, 2, v0
	global_load_dword v64, v[10:11], off
	global_load_dword v96, v[6:7], off
	v_lshl_add_u64 v[10:11], v[10:11], 0, s[8:9]
	global_load_dword v65, v[10:11], off
	global_load_dword v97, v[6:7], off offset:128
	v_lshl_add_u64 v[10:11], v[10:11], 0, s[8:9]
	global_load_dword v66, v[10:11], off
	global_load_dword v98, v[6:7], off offset:256
	v_lshl_add_u64 v[10:11], v[10:11], 0, s[8:9]
	global_load_dword v67, v[10:11], off
	global_load_dword v99, v[6:7], off offset:384
	v_lshl_add_u64 v[10:11], v[10:11], 0, s[8:9]
	global_load_dword v68, v[10:11], off
	global_load_dword v100, v[6:7], off offset:512
	v_lshl_add_u64 v[10:11], v[10:11], 0, s[8:9]
	global_load_dword v69, v[10:11], off
	global_load_dword v101, v[6:7], off offset:640
	v_lshl_add_u64 v[10:11], v[10:11], 0, s[8:9]
	global_load_dword v70, v[10:11], off
	global_load_dword v102, v[6:7], off offset:768
	v_lshl_add_u64 v[10:11], v[10:11], 0, s[8:9]
	global_load_dword v71, v[10:11], off
	global_load_dword v103, v[6:7], off offset:896
	v_lshl_add_u64 v[10:11], v[10:11], 0, s[8:9]
	global_load_dword v72, v[10:11], off
	global_load_dword v104, v[6:7], off offset:1024
	v_lshl_add_u64 v[10:11], v[10:11], 0, s[8:9]
	global_load_dword v73, v[10:11], off
	global_load_dword v105, v[6:7], off offset:1152
	v_lshl_add_u64 v[10:11], v[10:11], 0, s[8:9]
	global_load_dword v74, v[10:11], off
	global_load_dword v106, v[6:7], off offset:1280
	v_lshl_add_u64 v[10:11], v[10:11], 0, s[8:9]
	global_load_dword v75, v[10:11], off
	global_load_dword v107, v[6:7], off offset:1408
	v_lshl_add_u64 v[10:11], v[10:11], 0, s[8:9]
	global_load_dword v76, v[10:11], off
	global_load_dword v108, v[6:7], off offset:1536
	v_lshl_add_u64 v[10:11], v[10:11], 0, s[8:9]
	global_load_dword v77, v[10:11], off
	global_load_dword v109, v[6:7], off offset:1664
	v_lshl_add_u64 v[10:11], v[10:11], 0, s[8:9]
	global_load_dword v78, v[10:11], off
	global_load_dword v110, v[6:7], off offset:1792
	v_lshl_add_u64 v[10:11], v[10:11], 0, s[8:9]
	global_load_dword v79, v[10:11], off
	global_load_dword v111, v[6:7], off offset:1920
	v_lshl_add_u64 v[10:11], v[10:11], 0, s[8:9]
	s_waitcnt vmcnt(0)
	v_mul_f32_e32 v64, v64, v96
	ds_write_b32 v4, v64
	v_mul_f32_e32 v65, v65, v97
	ds_write_b32 v4, v65 offset:1024
	v_mul_f32_e32 v66, v66, v98
	ds_write_b32 v4, v66 offset:2048
	v_mul_f32_e32 v67, v67, v99
	ds_write_b32 v4, v67 offset:3072
	v_mul_f32_e32 v68, v68, v100
	ds_write_b32 v4, v68 offset:4096
	v_mul_f32_e32 v69, v69, v101
	ds_write_b32 v4, v69 offset:5120
	v_mul_f32_e32 v70, v70, v102
	ds_write_b32 v4, v70 offset:6144
	v_mul_f32_e32 v71, v71, v103
	ds_write_b32 v4, v71 offset:7168
	v_mul_f32_e32 v72, v72, v104
	ds_write_b32 v4, v72 offset:8192
	v_mul_f32_e32 v73, v73, v105
	ds_write_b32 v4, v73 offset:9216
	v_mul_f32_e32 v74, v74, v106
	ds_write_b32 v4, v74 offset:10240
	v_mul_f32_e32 v75, v75, v107
	ds_write_b32 v4, v75 offset:11264
	v_mul_f32_e32 v76, v76, v108
	ds_write_b32 v4, v76 offset:12288
	v_mul_f32_e32 v77, v77, v109
	ds_write_b32 v4, v77 offset:13312
	v_mul_f32_e32 v78, v78, v110
	ds_write_b32 v4, v78 offset:14336
	v_mul_f32_e32 v79, v79, v111
	ds_write_b32 v4, v79 offset:15360
	global_load_dword v80, v[10:11], off
	global_load_dword v112, v[6:7], off offset:2048
	v_lshl_add_u64 v[10:11], v[10:11], 0, s[8:9]
	global_load_dword v81, v[10:11], off
	global_load_dword v113, v[6:7], off offset:2176
	v_lshl_add_u64 v[10:11], v[10:11], 0, s[8:9]
	global_load_dword v82, v[10:11], off
	global_load_dword v114, v[6:7], off offset:2304
	v_lshl_add_u64 v[10:11], v[10:11], 0, s[8:9]
	global_load_dword v83, v[10:11], off
	global_load_dword v115, v[6:7], off offset:2432
	v_lshl_add_u64 v[10:11], v[10:11], 0, s[8:9]
	global_load_dword v84, v[10:11], off
	global_load_dword v116, v[6:7], off offset:2560
	v_lshl_add_u64 v[10:11], v[10:11], 0, s[8:9]
	global_load_dword v85, v[10:11], off
	global_load_dword v117, v[6:7], off offset:2688
	v_lshl_add_u64 v[10:11], v[10:11], 0, s[8:9]
	global_load_dword v86, v[10:11], off
	global_load_dword v118, v[6:7], off offset:2816
	v_lshl_add_u64 v[10:11], v[10:11], 0, s[8:9]
	global_load_dword v87, v[10:11], off
	global_load_dword v119, v[6:7], off offset:2944
	v_lshl_add_u64 v[10:11], v[10:11], 0, s[8:9]
	global_load_dword v88, v[10:11], off
	global_load_dword v120, v[6:7], off offset:3072
	v_lshl_add_u64 v[10:11], v[10:11], 0, s[8:9]
	global_load_dword v89, v[10:11], off
	global_load_dword v121, v[6:7], off offset:3200
	v_lshl_add_u64 v[10:11], v[10:11], 0, s[8:9]
	global_load_dword v90, v[10:11], off
	global_load_dword v122, v[6:7], off offset:3328
	v_lshl_add_u64 v[10:11], v[10:11], 0, s[8:9]
	global_load_dword v91, v[10:11], off
	global_load_dword v123, v[6:7], off offset:3456
	v_lshl_add_u64 v[10:11], v[10:11], 0, s[8:9]
	global_load_dword v92, v[10:11], off
	global_load_dword v124, v[6:7], off offset:3584
	v_lshl_add_u64 v[10:11], v[10:11], 0, s[8:9]
	global_load_dword v93, v[10:11], off
	global_load_dword v125, v[6:7], off offset:3712
	v_lshl_add_u64 v[10:11], v[10:11], 0, s[8:9]
	global_load_dword v94, v[10:11], off
	global_load_dword v126, v[6:7], off offset:3840
	v_lshl_add_u64 v[10:11], v[10:11], 0, s[8:9]
	global_load_dword v95, v[10:11], off
	global_load_dword v127, v[6:7], off offset:3968
	s_waitcnt vmcnt(0)
	v_mul_f32_e32 v80, v80, v112
	ds_write_b32 v4, v80 offset:16384
	v_mul_f32_e32 v81, v81, v113
	ds_write_b32 v4, v81 offset:17408
	v_mul_f32_e32 v82, v82, v114
	ds_write_b32 v4, v82 offset:18432
	v_mul_f32_e32 v83, v83, v115
	ds_write_b32 v4, v83 offset:19456
	v_mul_f32_e32 v84, v84, v116
	ds_write_b32 v4, v84 offset:20480
	v_mul_f32_e32 v85, v85, v117
	ds_write_b32 v4, v85 offset:21504
	v_mul_f32_e32 v86, v86, v118
	ds_write_b32 v4, v86 offset:22528
	v_mul_f32_e32 v87, v87, v119
	ds_write_b32 v4, v87 offset:23552
	v_mul_f32_e32 v88, v88, v120
	ds_write_b32 v4, v88 offset:24576
	v_mul_f32_e32 v89, v89, v121
	ds_write_b32 v4, v89 offset:25600
	v_mul_f32_e32 v90, v90, v122
	ds_write_b32 v4, v90 offset:26624
	v_mul_f32_e32 v91, v91, v123
	ds_write_b32 v4, v91 offset:27648
	v_mul_f32_e32 v92, v92, v124
	ds_write_b32 v4, v92 offset:28672
	v_mul_f32_e32 v93, v93, v125
	ds_write_b32 v4, v93 offset:29696
	v_mul_f32_e32 v94, v94, v126
	ds_write_b32 v4, v94 offset:30720
	v_mul_f32_e32 v95, v95, v127
	ds_write_b32 v4, v95 offset:31744
